# out-proj phase start stagger retuned (14 instead of 10 sleep units) for the shorter unrolled tiles
# speedup vs baseline: 1.0060x; 1.0023x over previous
.LBB0_864:
	s_or_b64 exec, exec, s[0:1]
	v_readlane_b32 s0, v247, 4
	s_mul_hi_u32 s0, s0, 0x210
	v_readlane_b32 s3, v247, 5
	s_mul_i32 s0, s0, s3
	s_sub_i32 s0, 0x210, s0
	s_sub_i32 s1, s0, s3
	s_cmp_ge_u32 s0, s3
	s_cselect_b32 s0, s1, s0
	s_sub_i32 s1, s0, s3
	s_cmp_ge_u32 s0, s3
	s_cselect_b32 s33, s1, s0
	s_sub_i32 s3, 0x210, s33
	s_cmp_ge_i32 s2, s3
	v_lshrrev_b32_e32 v70, 3, v184
	v_lshlrev_b32_e32 v71, 2, v184
	s_barrier
	s_cbranch_scc1 .LBB0_873
	v_readlane_b32 s0, v247, 0
	v_readlane_b32 s1, v247, 1
	s_add_u32 s0, s0, 8
	s_addc_u32 s1, s1, 0
	s_add_u32 s38, s54, 0x2b75100
	s_addc_u32 s39, s55, 0
	s_add_u32 s40, s54, 0x975100
	s_addc_u32 s41, s55, 0
	v_and_b32_e32 v0, 4, v70
	v_lshl_or_b32 v75, v209, 10, v188
	s_add_u32 s42, s52, 0x4000000
	v_and_b32_e32 v72, 0x7c, v71
	v_mul_u32_u24_e32 v73, 0x110, v209
	v_mul_u32_u24_e32 v74, 0x110, v0
	v_or_b32_e32 v76, 0x1000, v75
	v_or_b32_e32 v77, 0x2000, v75
	v_or_b32_e32 v78, 0x3000, v75
	v_or_b32_e32 v79, 0x4000, v75
	v_or_b32_e32 v80, 0x5000, v75
	v_or_b32_e32 v81, 0x6000, v75
	v_or_b32_e32 v82, 0x7000, v75
	s_addc_u32 s43, s53, 0
	s_lshl_b32 s44, s2, 8
	s_lshl_b32 s45, s86, 8
	s_mov_b32 s5, 0
	v_mov_b32_e32 v69, 0
	s_mov_b64 s[6:7], 0x20000
	s_mov_b64 s[8:9], 0x40000
	s_mov_b64 s[10:11], 0x60000
	s_mov_b32 s46, 0xa000
	s_mov_b64 s[12:13], 0x2b75180
	s_mov_b64 s[14:15], 0x2b95180
	s_mov_b64 s[16:17], 0x975180
	s_mov_b64 s[18:19], 0x995180
	s_mov_b64 s[20:21], 0x9b5180
	s_mov_b64 s[22:23], 0x9d5180
	s_mov_b32 s47, s2
	s_cmp_lt_u32 s2, 0x80
	s_cbranch_scc1 .LBB0_868
	s_movk_i32 s20, 14
